# mLSTM chunk step: lane^16 / lane^32 partial sums via v_permlane16_swap / v_permlane32_swap on register copies, 8-lane sums via DPP moves (were ds_bpermute round trips on the serial chain)
# baseline (speedup 1.0000x reference)
; __device__ __forceinline__ void mlstm_item8(const Params& p, unsigned char* lds, int item) {
;     ...
;       const int t = 16 * tt + fr; const float rt = rowt[t]; float ds = 0.f;
; #pragma unroll
;       for (int r = 0; r < 4; ++r) { const int sI = 16 * st + 4 * fq + r; float v = 0.f; if (sI <= t) v = S[r] * __expf(rt + cols[sI]); S[r] = v; ds += v; }
;       ds += __shfl_xor(ds, 16); ds += __shfl_xor(ds, 32);
;       if (fq == 0) dpart[st * 64 + t] = ds;
.LBB0_374:
	s_or_b64 exec, exec, s[0:1]
	s_waitcnt lgkmcnt(0)
	v_mbcnt_hi_u32_b32 v40, -1, v160
	v_and_b32_e32 v43, 64, v40
	v_add_f32_e32 v38, 0, v42
	v_xor_b32_e32 v39, 16, v40
	v_add_u32_e32 v52, 64, v43
	v_add_f32_e32 v38, v38, v36
	v_cmp_lt_i32_e32 vcc, v39, v52
	v_add_f32_e32 v38, v38, v41
	v_add_f32_e32 v38, v38, v37
	v_cndmask_b32_e32 v39, v40, v39, vcc
	v_lshlrev_b32_e32 v39, 2, v39
	v_mov_b32_e32 v250, v38
	v_mov_b32_e32 v39, v38
	s_nop 1
	v_permlane16_swap_b32_e32 v39, v250
	s_waitcnt lgkmcnt(0)
	v_add_f32_e32 v38, v250, v39
	v_xor_b32_e32 v39, 32, v40
	v_cmp_lt_i32_e32 vcc, v39, v52
	s_nop 1
	v_cndmask_b32_e32 v39, v40, v39, vcc
	v_lshlrev_b32_e32 v39, 2, v39
	v_mov_b32_e32 v250, v38
	v_mov_b32_e32 v39, v38
	s_nop 1
	v_permlane32_swap_b32_e32 v39, v250
	s_and_saveexec_b64 s[0:1], s[14:15]
	s_cbranch_execz .LBB0_376
	s_waitcnt lgkmcnt(0)
	v_add_f32_e32 v38, v250, v39
	ds_write_b32 v96, v38 offset:640

; #define MFMA(a, b, c) __builtin_amdgcn_mfma_f32_16x16x32_bf16((a), (b), (c), 0, 0, 0)
; __device__ __forceinline__ void mlstm_item8(const Params& p, unsigned char* lds, int item) {
;     ...
;     auto stile = [&](const int st, const int tt) {
;       f32x4 S = (f32x4){0.f, 0.f, 0.f, 0.f};
; #pragma unroll
;       for (int ks = 0; ks < 4; ++ks) { const bf16x8 ak = *(const bf16x8*)(Ks + (16 * st + fr) * 136 + 32 * ks + 8 * fq); const bf16x8 bq = *(const bf16x8*)(Qs + (16 * tt + fr) * 136 + 32 * ks + 8 * fq); S = MFMA(ak, bq, S); }
;       const int t = 16 * tt + fr; const float rt = rowt[t]; float ds = 0.f;
; #pragma unroll
;       for (int r = 0; r < 4; ++r) { const int sI = 16 * st + 4 * fq + r; float v = 0.f; if (sI <= t) v = S[r] * __expf(rt + cols[sI]); S[r] = v; ds += v; }
;       ds += __shfl_xor(ds, 16); ds += __shfl_xor(ds, 32);
;       if (fq == 0) dpart[st * 64 + t] = ds;
.LBB0_378:
	s_waitcnt lgkmcnt(1)
	ds_read_b128 v[36:39], v99 offset:21760
	ds_read_b128 v[40:43], v91
	s_waitcnt lgkmcnt(0)
	v_mfma_f32_16x16x32_bf16 v[36:39], v[36:39], v[40:43], 0
	ds_read_b128 v[40:43], v99 offset:21824
	ds_read_b128 v[44:47], v91 offset:64
	s_waitcnt lgkmcnt(0)
	v_mfma_f32_16x16x32_bf16 v[36:39], v[40:43], v[44:47], v[36:39]
	ds_read_b128 v[40:43], v99 offset:21888
	ds_read_b128 v[44:47], v91 offset:128
	s_waitcnt lgkmcnt(0)
	v_mfma_f32_16x16x32_bf16 v[36:39], v[40:43], v[44:47], v[36:39]
	ds_read_b128 v[40:43], v99 offset:21952
	ds_read_b128 v[44:47], v91 offset:192
	s_waitcnt lgkmcnt(0)
	v_mfma_f32_16x16x32_bf16 v[36:39], v[40:43], v[44:47], v[36:39]
	ds_read_b32 v40, v92
	ds_read_b128 v[42:45], v93 offset:64
	s_waitcnt lgkmcnt(0)
	v_add_f32_e32 v41, v40, v42
	v_mul_f32_e32 v41, 0x3fb8aa3b, v41
	v_add_f32_e32 v42, v40, v43
	v_exp_f32_e32 v41, v41
	v_mul_f32_e32 v42, 0x3fb8aa3b, v42
	v_add_f32_e32 v43, v40, v44
	v_add_f32_e32 v40, v40, v45
	v_exp_f32_e32 v42, v42
	v_mul_f32_e32 v43, 0x3fb8aa3b, v43
	v_mul_f32_e32 v40, 0x3fb8aa3b, v40
	v_exp_f32_e32 v43, v43
	v_exp_f32_e32 v44, v40
	v_mbcnt_hi_u32_b32 v40, -1, v160
	v_and_b32_e32 v47, 64, v40
	v_fma_f32 v46, v36, v41, 0
	v_xor_b32_e32 v45, 16, v40
	v_add_u32_e32 v52, 64, v47
	v_fmac_f32_e32 v46, v37, v42
	v_cmp_lt_i32_e32 vcc, v45, v52
	v_fmac_f32_e32 v46, v38, v43
	v_fmac_f32_e32 v46, v39, v44
	v_cndmask_b32_e32 v45, v40, v45, vcc
	v_lshlrev_b32_e32 v45, 2, v45
	v_mov_b32_e32 v250, v46
	v_mov_b32_e32 v45, v46
	s_nop 1
	v_permlane16_swap_b32_e32 v45, v250
	s_waitcnt lgkmcnt(0)
	v_add_f32_e32 v45, v250, v45
	v_xor_b32_e32 v46, 32, v40
	v_cmp_lt_i32_e32 vcc, v46, v52
	s_nop 1
	v_cndmask_b32_e32 v46, v40, v46, vcc
	v_lshlrev_b32_e32 v46, 2, v46
	v_mov_b32_e32 v250, v45
	v_mov_b32_e32 v46, v45
	s_nop 1
	v_permlane32_swap_b32_e32 v46, v250
	s_and_saveexec_b64 s[46:47], s[14:15]
	s_cbranch_execz .LBB0_380
	s_waitcnt lgkmcnt(0)
	v_add_f32_e32 v45, v250, v46
	ds_write_b32 v96, v45 offset:384

; #define MFMA(a, b, c) __builtin_amdgcn_mfma_f32_16x16x32_bf16((a), (b), (c), 0, 0, 0)
; __device__ __forceinline__ void mlstm_item8(const Params& p, unsigned char* lds, int item) {
;     ...
;     auto stile = [&](const int st, const int tt) {
;       f32x4 S = (f32x4){0.f, 0.f, 0.f, 0.f};
; #pragma unroll
;       for (int ks = 0; ks < 4; ++ks) { const bf16x8 ak = *(const bf16x8*)(Ks + (16 * st + fr) * 136 + 32 * ks + 8 * fq); const bf16x8 bq = *(const bf16x8*)(Qs + (16 * tt + fr) * 136 + 32 * ks + 8 * fq); S = MFMA(ak, bq, S); }
;       const int t = 16 * tt + fr; const float rt = rowt[t]; float ds = 0.f;
; #pragma unroll
;       for (int r = 0; r < 4; ++r) { const int sI = 16 * st + 4 * fq + r; float v = 0.f; if (sI <= t) v = S[r] * __expf(rt + cols[sI]); S[r] = v; ds += v; }
;       ds += __shfl_xor(ds, 16); ds += __shfl_xor(ds, 32);
;       if (fq == 0) dpart[st * 64 + t] = ds;
.LBB0_382:
	s_waitcnt lgkmcnt(1)
	ds_read_b128 v[36:39], v99 offset:17408
	ds_read_b128 v[40:43], v91
	s_waitcnt lgkmcnt(0)
	v_mfma_f32_16x16x32_bf16 v[36:39], v[36:39], v[40:43], 0
	ds_read_b128 v[40:43], v99 offset:17472
	ds_read_b128 v[44:47], v91 offset:64
	s_waitcnt lgkmcnt(0)
	v_mfma_f32_16x16x32_bf16 v[36:39], v[40:43], v[44:47], v[36:39]
	ds_read_b128 v[40:43], v99 offset:17536
	ds_read_b128 v[44:47], v91 offset:128
	s_waitcnt lgkmcnt(0)
	v_mfma_f32_16x16x32_bf16 v[36:39], v[40:43], v[44:47], v[36:39]
	ds_read_b128 v[40:43], v99 offset:17600
	ds_read_b128 v[44:47], v91 offset:192
	s_waitcnt lgkmcnt(0)
	v_mfma_f32_16x16x32_bf16 v[36:39], v[40:43], v[44:47], v[36:39]
	ds_read_b32 v40, v92
	ds_read_b128 v[44:47], v93
	s_waitcnt lgkmcnt(0)
	v_add_f32_e32 v41, v40, v44
	v_mul_f32_e32 v41, 0x3fb8aa3b, v41
	v_exp_f32_e32 v43, v41
	v_add_f32_e32 v41, v40, v45
	v_mul_f32_e32 v41, 0x3fb8aa3b, v41
	v_exp_f32_e32 v44, v41
	v_add_f32_e32 v41, v40, v46
	v_add_f32_e32 v40, v40, v47
	v_mul_f32_e32 v41, 0x3fb8aa3b, v41
	v_mul_f32_e32 v40, 0x3fb8aa3b, v40
	v_exp_f32_e32 v45, v41
	v_exp_f32_e32 v46, v40
	v_mbcnt_hi_u32_b32 v40, -1, v160
	v_and_b32_e32 v47, 64, v40
	v_fma_f32 v42, v36, v43, 0
	v_xor_b32_e32 v41, 16, v40
	v_add_u32_e32 v52, 64, v47
	v_fmac_f32_e32 v42, v37, v44
	v_cmp_lt_i32_e32 vcc, v41, v52
	v_fmac_f32_e32 v42, v38, v45
	v_fmac_f32_e32 v42, v39, v46
	v_cndmask_b32_e32 v41, v40, v41, vcc
	v_lshlrev_b32_e32 v41, 2, v41
	v_mov_b32_e32 v250, v42
	v_mov_b32_e32 v47, v42
	s_nop 1
	v_permlane16_swap_b32_e32 v47, v250
	s_waitcnt lgkmcnt(0)
	v_add_f32_e32 v47, v250, v47
	v_xor_b32_e32 v42, 32, v40
	v_cmp_lt_i32_e32 vcc, v42, v52
	s_nop 1
	v_cndmask_b32_e32 v42, v40, v42, vcc
	v_lshlrev_b32_e32 v42, 2, v42
	v_mov_b32_e32 v250, v47
	v_mov_b32_e32 v48, v47
	s_nop 1
	v_permlane32_swap_b32_e32 v48, v250
	s_and_saveexec_b64 s[46:47], s[14:15]
	s_cbranch_execz .LBB0_384
	s_waitcnt lgkmcnt(0)
	v_add_f32_e32 v47, v250, v48
	ds_write_b32 v100, v47

; __device__ __forceinline__ void mlstm_item8(const Params& p, unsigned char* lds, int item) {
;     ...
;       const int t = 16 * tt + fr; const float rt = rowt[t]; float ds = 0.f;
; #pragma unroll
;       for (int r = 0; r < 4; ++r) { const int sI = 16 * st + 4 * fq + r; float v = 0.f; if (sI <= t) v = S[r] * __expf(rt + cols[sI]); S[r] = v; ds += v; }
;       ds += __shfl_xor(ds, 16); ds += __shfl_xor(ds, 32);
;       if (fq == 0) dpart[st * 64 + t] = ds;
.LBB0_392:
	s_or_b64 exec, exec, s[46:47]
	v_add_f32_e32 v38, 0, v44
	v_add_f32_e32 v38, v38, v36
	v_add_f32_e32 v38, v38, v43
	v_add_f32_e32 v38, v38, v37
	v_mov_b32_e32 v250, v38
	v_mov_b32_e32 v39, v38
	s_nop 1
	v_permlane16_swap_b32_e32 v39, v250
	s_waitcnt lgkmcnt(0)
	v_add_f32_e32 v38, v250, v39
	v_mov_b32_e32 v250, v38
	v_mov_b32_e32 v39, v38
	s_nop 1
	v_permlane32_swap_b32_e32 v39, v250
	s_and_saveexec_b64 s[46:47], s[14:15]
	s_cbranch_execz .LBB0_394
	s_waitcnt lgkmcnt(0)
	v_add_f32_e32 v38, v250, v39
	ds_write_b32 v96, v38 offset:960

; DEVI unsigned pk_bf16(float lo, float hi) { unsigned r; asm("v_cvt_pk_bf16_f32 %0, %1, %2" : "=v"(r) : "v"(lo), "v"(hi)); return r; }
; #define MFMA(a, b, c) __builtin_amdgcn_mfma_f32_16x16x32_bf16((a), (b), (c), 0, 0, 0)
; __device__ __forceinline__ void mlstm_item8(const Params& p, unsigned char* lds, int item) {
;     ...
;     auto stile = [&](const int st, const int tt) {
;       f32x4 S = (f32x4){0.f, 0.f, 0.f, 0.f};
; #pragma unroll
;       for (int ks = 0; ks < 4; ++ks) { const bf16x8 ak = *(const bf16x8*)(Ks + (16 * st + fr) * 136 + 32 * ks + 8 * fq); const bf16x8 bq = *(const bf16x8*)(Qs + (16 * tt + fr) * 136 + 32 * ks + 8 * fq); S = MFMA(ak, bq, S); }
;       const int t = 16 * tt + fr; const float rt = rowt[t]; float ds = 0.f;
; #pragma unroll
;       for (int r = 0; r < 4; ++r) { const int sI = 16 * st + 4 * fq + r; float v = 0.f; if (sI <= t) v = S[r] * __expf(rt + cols[sI]); S[r] = v; ds += v; }
;       ds += __shfl_xor(ds, 16); ds += __shfl_xor(ds, 32);
;       if (fq == 0) dpart[st * 64 + t] = ds;
;       uint2 wv; wv.x = pk_bf16(S[0], S[1]); wv.y = pk_bf16(S[2], S[3]);
;       *(uint2*)(Sp + t * 72 + 16 * st + 4 * fq) = wv;
.LBB0_407:
	s_or_b64 exec, exec, s[44:45]
	s_waitcnt lgkmcnt(0)
	v_mbcnt_hi_u32_b32 v40, -1, v160
	v_and_b32_e32 v41, 64, v40
	v_add_f32_e32 v38, 0, v44
	v_xor_b32_e32 v39, 16, v40
	v_add_u32_e32 v52, 64, v41
	v_add_f32_e32 v38, v38, v36
	v_cmp_lt_i32_e32 vcc, v39, v52
	v_add_f32_e32 v38, v38, v43
	v_add_f32_e32 v38, v38, v37
	v_cndmask_b32_e32 v39, v40, v39, vcc
	v_lshlrev_b32_e32 v41, 2, v39
	v_mov_b32_e32 v250, v38
	v_mov_b32_e32 v39, v38
	s_nop 1
	v_permlane16_swap_b32_e32 v39, v250
	s_waitcnt lgkmcnt(0)
	v_add_f32_e32 v38, v250, v39
	v_xor_b32_e32 v39, 32, v40
	v_cmp_lt_i32_e32 vcc, v39, v52
	s_nop 1
	v_cndmask_b32_e32 v39, v40, v39, vcc
	v_lshlrev_b32_e32 v42, 2, v39
	v_mov_b32_e32 v250, v38
	v_mov_b32_e32 v39, v38
	s_nop 1
	v_permlane32_swap_b32_e32 v39, v250
	s_and_saveexec_b64 s[44:45], s[14:15]
	s_cbranch_execz .LBB0_409
	s_waitcnt lgkmcnt(0)
	v_add_f32_e32 v38, v250, v39
	ds_write_b32 v96, v38 offset:320
.LBB0_409:
	s_or_b64 exec, exec, s[44:45]
	v_cvt_pk_bf16_f32 v36, v44, v36
	v_cvt_pk_bf16_f32 v37, v43, v37
	ds_write_b64 v110, v[36:37] offset:32
	s_waitcnt lgkmcnt(1)
	ds_read_b128 v[36:39], v99 offset:26112
	ds_read_b128 v[44:47], v101
	s_waitcnt lgkmcnt(0)
	v_mfma_f32_16x16x32_bf16 v[36:39], v[36:39], v[44:47], 0
	ds_read_b128 v[44:47], v99 offset:26176
	ds_read_b128 v[48:51], v101 offset:64
	s_waitcnt lgkmcnt(0)
	v_mfma_f32_16x16x32_bf16 v[36:39], v[44:47], v[48:51], v[36:39]
	ds_read_b128 v[44:47], v99 offset:26240
	ds_read_b128 v[48:51], v101 offset:128
	s_waitcnt lgkmcnt(0)
	v_mfma_f32_16x16x32_bf16 v[36:39], v[44:47], v[48:51], v[36:39]
	ds_read_b128 v[44:47], v99 offset:26304
	ds_read_b128 v[48:51], v101 offset:192
	s_waitcnt lgkmcnt(0)
	v_mfma_f32_16x16x32_bf16 v[36:39], v[44:47], v[48:51], v[36:39]
	ds_read_b32 v48, v102
	ds_read_b128 v[44:47], v93 offset:128
	s_waitcnt lgkmcnt(0)
	v_add_f32_e32 v43, v48, v44
	v_mul_f32_e32 v43, 0x3fb8aa3b, v43
	v_add_f32_e32 v44, v48, v45
	v_exp_f32_e32 v43, v43
	v_mul_f32_e32 v44, 0x3fb8aa3b, v44
	v_add_f32_e32 v45, v48, v46
	v_exp_f32_e32 v44, v44
	v_mul_f32_e32 v45, 0x3fb8aa3b, v45
	v_add_f32_e32 v46, v48, v47
	v_exp_f32_e32 v45, v45
	v_mul_f32_e32 v46, 0x3fb8aa3b, v46
	v_exp_f32_e32 v46, v46
	v_fma_f32 v49, v36, v43, 0
	v_fmac_f32_e32 v49, v37, v44
	v_fmac_f32_e32 v49, v38, v45
	v_fmac_f32_e32 v49, v39, v46
	v_mov_b32_e32 v250, v49
	v_mov_b32_e32 v41, v49
	s_nop 1
	v_permlane16_swap_b32_e32 v41, v250
	s_waitcnt lgkmcnt(0)
	v_add_f32_e32 v41, v250, v41
	v_mov_b32_e32 v250, v41
	v_mov_b32_e32 v42, v41
	s_nop 1
	v_permlane32_swap_b32_e32 v42, v250
	s_and_saveexec_b64 s[44:45], s[14:15]
	s_cbranch_execz .LBB0_411
	s_waitcnt lgkmcnt(0)
	v_add_f32_e32 v41, v250, v42
	ds_write_b32 v96, v41 offset:704

; DEVI unsigned pk_bf16(float lo, float hi) { unsigned r; asm("v_cvt_pk_bf16_f32 %0, %1, %2" : "=v"(r) : "v"(lo), "v"(hi)); return r; }
; #define MFMA(a, b, c) __builtin_amdgcn_mfma_f32_16x16x32_bf16((a), (b), (c), 0, 0, 0)
; __device__ __forceinline__ void mlstm_item8(const Params& p, unsigned char* lds, int item) {
;     ...
;     auto stile = [&](const int st, const int tt) {
;       f32x4 S = (f32x4){0.f, 0.f, 0.f, 0.f};
; #pragma unroll
;       for (int ks = 0; ks < 4; ++ks) { const bf16x8 ak = *(const bf16x8*)(Ks + (16 * st + fr) * 136 + 32 * ks + 8 * fq); const bf16x8 bq = *(const bf16x8*)(Qs + (16 * tt + fr) * 136 + 32 * ks + 8 * fq); S = MFMA(ak, bq, S); }
;       const int t = 16 * tt + fr; const float rt = rowt[t]; float ds = 0.f;
; #pragma unroll
;       for (int r = 0; r < 4; ++r) { const int sI = 16 * st + 4 * fq + r; float v = 0.f; if (sI <= t) v = S[r] * __expf(rt + cols[sI]); S[r] = v; ds += v; }
;       ds += __shfl_xor(ds, 16); ds += __shfl_xor(ds, 32);
;       if (fq == 0) dpart[st * 64 + t] = ds;
;       uint2 wv; wv.x = pk_bf16(S[0], S[1]); wv.y = pk_bf16(S[2], S[3]);
;       *(uint2*)(Sp + t * 72 + 16 * st + 4 * fq) = wv;
;     };
;     if (w == 0) { stile(0, 0); stile(0, 3); }
;     else if (w == 1) { stile(0, 1); stile(1, 3); }
;     else if (w == 2) { stile(1, 1); stile(2, 3); }
;     else if (w == 3) { stile(0, 2); stile(3, 3); }
.LBB0_412:
	s_and_b64 vcc, exec, s[44:45]
	s_cbranch_vccz .LBB0_418
	s_waitcnt lgkmcnt(1)
	ds_read_b128 v[36:39], v99 offset:17408
	ds_read_b128 v[40:43], v106
	s_waitcnt lgkmcnt(0)
	v_mfma_f32_16x16x32_bf16 v[36:39], v[36:39], v[40:43], 0
	ds_read_b128 v[40:43], v99 offset:17472
	ds_read_b128 v[44:47], v106 offset:64
	s_waitcnt lgkmcnt(0)
	v_mfma_f32_16x16x32_bf16 v[36:39], v[40:43], v[44:47], v[36:39]
	ds_read_b128 v[40:43], v99 offset:17536
	ds_read_b128 v[44:47], v106 offset:128
	s_waitcnt lgkmcnt(0)
	v_mfma_f32_16x16x32_bf16 v[36:39], v[40:43], v[44:47], v[36:39]
	ds_read_b128 v[40:43], v99 offset:17600
	ds_read_b128 v[44:47], v106 offset:192
	s_waitcnt lgkmcnt(0)
	v_mfma_f32_16x16x32_bf16 v[36:39], v[40:43], v[44:47], v[36:39]
	ds_read_b32 v40, v107
	ds_read_b128 v[44:47], v93
	s_waitcnt lgkmcnt(0)
	v_add_f32_e32 v41, v40, v44
	v_mul_f32_e32 v41, 0x3fb8aa3b, v41
	v_exp_f32_e32 v43, v41
	v_add_f32_e32 v41, v40, v45
	v_mul_f32_e32 v41, 0x3fb8aa3b, v41
	v_exp_f32_e32 v44, v41
	v_add_f32_e32 v41, v40, v46
	v_add_f32_e32 v40, v40, v47
	v_mul_f32_e32 v41, 0x3fb8aa3b, v41
	v_mul_f32_e32 v40, 0x3fb8aa3b, v40
	v_exp_f32_e32 v45, v41
	v_exp_f32_e32 v46, v40
	v_mbcnt_hi_u32_b32 v40, -1, v160
	v_and_b32_e32 v47, 64, v40
	v_fma_f32 v42, v36, v43, 0
	v_xor_b32_e32 v41, 16, v40
	v_add_u32_e32 v52, 64, v47
	v_fmac_f32_e32 v42, v37, v44
	v_cmp_lt_i32_e32 vcc, v41, v52
	v_fmac_f32_e32 v42, v38, v45
	v_fmac_f32_e32 v42, v39, v46
	v_cndmask_b32_e32 v41, v40, v41, vcc
	v_lshlrev_b32_e32 v41, 2, v41
	v_mov_b32_e32 v250, v42
	v_mov_b32_e32 v47, v42
	s_nop 1
	v_permlane16_swap_b32_e32 v47, v250
	s_waitcnt lgkmcnt(0)
	v_add_f32_e32 v47, v250, v47
	v_xor_b32_e32 v42, 32, v40
	v_cmp_lt_i32_e32 vcc, v42, v52
	s_nop 1
	v_cndmask_b32_e32 v42, v40, v42, vcc
	v_lshlrev_b32_e32 v42, 2, v42
	v_mov_b32_e32 v250, v47
	v_mov_b32_e32 v48, v47
	s_nop 1
	v_permlane32_swap_b32_e32 v48, v250
	s_and_saveexec_b64 s[44:45], s[14:15]
	s_cbranch_execz .LBB0_415
	s_waitcnt lgkmcnt(0)
	v_add_f32_e32 v47, v250, v48
	ds_write_b32 v111, v47
.LBB0_415:
	s_or_b64 exec, exec, s[44:45]
	v_mul_f32_e32 v36, v36, v43
	v_mul_f32_e32 v37, v37, v44
	v_mul_f32_e32 v38, v38, v45
	v_mul_f32_e32 v39, v39, v46
	v_cvt_pk_bf16_f32 v36, v36, v37
	v_cvt_pk_bf16_f32 v37, v38, v39
	ds_write_b64 v110, v[36:37]
	ds_read_b128 v[36:39], v106 offset:17408
	ds_read_b128 v[44:47], v101
	s_waitcnt lgkmcnt(0)
	v_mfma_f32_16x16x32_bf16 v[36:39], v[36:39], v[44:47], 0
	ds_read_b128 v[44:47], v106 offset:17472
	ds_read_b128 v[48:51], v101 offset:64
	s_waitcnt lgkmcnt(0)
	v_mfma_f32_16x16x32_bf16 v[36:39], v[44:47], v[48:51], v[36:39]
	ds_read_b128 v[44:47], v106 offset:17536
	ds_read_b128 v[48:51], v101 offset:128
	s_waitcnt lgkmcnt(0)
	v_mfma_f32_16x16x32_bf16 v[36:39], v[44:47], v[48:51], v[36:39]
	ds_read_b128 v[44:47], v106 offset:17600
	ds_read_b128 v[48:51], v101 offset:192
	s_waitcnt lgkmcnt(0)
	v_mfma_f32_16x16x32_bf16 v[36:39], v[44:47], v[48:51], v[36:39]
	ds_read_b32 v48, v102
	ds_read_b128 v[44:47], v93 offset:64
	s_waitcnt lgkmcnt(0)
	v_add_f32_e32 v43, v48, v44
	v_mul_f32_e32 v43, 0x3fb8aa3b, v43
	v_add_f32_e32 v44, v48, v45
	v_exp_f32_e32 v43, v43
	v_mul_f32_e32 v44, 0x3fb8aa3b, v44
	v_add_f32_e32 v45, v48, v46
	v_exp_f32_e32 v44, v44
	v_mul_f32_e32 v45, 0x3fb8aa3b, v45
	v_add_f32_e32 v46, v48, v47
	v_exp_f32_e32 v45, v45
	v_mul_f32_e32 v46, 0x3fb8aa3b, v46
	v_exp_f32_e32 v46, v46
	v_fma_f32 v49, v36, v43, 0
	v_fmac_f32_e32 v49, v37, v44
	v_fmac_f32_e32 v49, v38, v45
	v_fmac_f32_e32 v49, v39, v46
	v_mov_b32_e32 v250, v49
	v_mov_b32_e32 v41, v49
	s_nop 1
	v_permlane16_swap_b32_e32 v41, v250
	s_waitcnt lgkmcnt(0)
	v_add_f32_e32 v41, v250, v41
	v_mov_b32_e32 v250, v41
	v_mov_b32_e32 v42, v41
	s_nop 1
	v_permlane32_swap_b32_e32 v42, v250
	s_and_saveexec_b64 s[44:45], s[14:15]
	s_cbranch_execz .LBB0_417
	s_waitcnt lgkmcnt(0)
	v_add_f32_e32 v41, v250, v42
	ds_write_b32 v96, v41 offset:448

; DEVI unsigned pk_bf16(float lo, float hi) { unsigned r; asm("v_cvt_pk_bf16_f32 %0, %1, %2" : "=v"(r) : "v"(lo), "v"(hi)); return r; }
; #define MFMA(a, b, c) __builtin_amdgcn_mfma_f32_16x16x32_bf16((a), (b), (c), 0, 0, 0)
; __device__ __forceinline__ void mlstm_item8(const Params& p, unsigned char* lds, int item) {
;     ...
;     auto stile = [&](const int st, const int tt) {
;       f32x4 S = (f32x4){0.f, 0.f, 0.f, 0.f};
; #pragma unroll
;       for (int ks = 0; ks < 4; ++ks) { const bf16x8 ak = *(const bf16x8*)(Ks + (16 * st + fr) * 136 + 32 * ks + 8 * fq); const bf16x8 bq = *(const bf16x8*)(Qs + (16 * tt + fr) * 136 + 32 * ks + 8 * fq); S = MFMA(ak, bq, S); }
;       const int t = 16 * tt + fr; const float rt = rowt[t]; float ds = 0.f;
; #pragma unroll
;       for (int r = 0; r < 4; ++r) { const int sI = 16 * st + 4 * fq + r; float v = 0.f; if (sI <= t) v = S[r] * __expf(rt + cols[sI]); S[r] = v; ds += v; }
;       ds += __shfl_xor(ds, 16); ds += __shfl_xor(ds, 32);
;       if (fq == 0) dpart[st * 64 + t] = ds;
;       uint2 wv; wv.x = pk_bf16(S[0], S[1]); wv.y = pk_bf16(S[2], S[3]);
;       *(uint2*)(Sp + t * 72 + 16 * st + 4 * fq) = wv;
.LBB0_432:
	s_or_b64 exec, exec, s[0:1]
	v_add_f32_e32 v52, 0, v161
	v_add_f32_e32 v52, v52, v162
	v_add_f32_e32 v52, v52, v159
	v_add_f32_e32 v54, v52, v164
	v_xor_b32_e32 v53, 16, v71
	v_add_u32_e32 v52, 64, v72
	v_cmp_lt_i32_e32 vcc, v53, v52
	s_nop 1
	v_cndmask_b32_e32 v53, v71, v53, vcc
	v_lshlrev_b32_e32 v53, 2, v53
	v_mov_b32_e32 v250, v54
	v_mov_b32_e32 v55, v54
	s_nop 1
	v_permlane16_swap_b32_e32 v55, v250
	s_waitcnt lgkmcnt(0)
	v_add_f32_e32 v55, v250, v55
	v_xor_b32_e32 v54, 32, v71
	v_cmp_lt_i32_e32 vcc, v54, v52
	s_nop 1
	v_cndmask_b32_e32 v54, v71, v54, vcc
	v_lshlrev_b32_e32 v54, 2, v54
	v_mov_b32_e32 v250, v55
	v_mov_b32_e32 v163, v55
	s_nop 1
	v_permlane32_swap_b32_e32 v163, v250
	s_and_saveexec_b64 s[0:1], s[14:15]
	s_cbranch_execz .LBB0_434
	s_waitcnt lgkmcnt(0)
	v_add_f32_e32 v55, v250, v163
	ds_write_b32 v96, v55
.LBB0_434:
	s_or_b64 exec, exec, s[0:1]
	v_cvt_pk_bf16_f32 v162, v161, v162
	s_waitcnt lgkmcnt(0)
	v_cvt_pk_bf16_f32 v163, v159, v164
	ds_write_b64 v116, v[162:163]
	ds_read_b128 v[162:165], v101
	s_waitcnt lgkmcnt(0)
	v_mfma_f32_16x16x32_bf16 v[36:39], v[36:39], v[162:165], 0
	ds_read_b128 v[162:165], v101 offset:64
	s_waitcnt lgkmcnt(0)
	v_mfma_f32_16x16x32_bf16 v[36:39], v[40:43], v[162:165], v[36:39]
	ds_read_b128 v[40:43], v101 offset:128
	s_waitcnt lgkmcnt(0)
	v_mfma_f32_16x16x32_bf16 v[36:39], v[44:47], v[40:43], v[36:39]
	ds_read_b128 v[40:43], v101 offset:192
	s_waitcnt lgkmcnt(0)
	v_mfma_f32_16x16x32_bf16 v[36:39], v[48:51], v[40:43], v[36:39]
	ds_read_b32 v44, v102
	ds_read_b128 v[40:43], v93
	s_waitcnt lgkmcnt(0)
	v_add_f32_e32 v40, v44, v40
	v_mul_f32_e32 v40, 0x3fb8aa3b, v40
	v_add_f32_e32 v41, v44, v41
	v_exp_f32_e32 v40, v40
	v_mul_f32_e32 v41, 0x3fb8aa3b, v41
	v_add_f32_e32 v42, v44, v42
	v_exp_f32_e32 v41, v41
	v_mul_f32_e32 v42, 0x3fb8aa3b, v42
	v_add_f32_e32 v43, v44, v43
	v_exp_f32_e32 v42, v42
	v_mul_f32_e32 v43, 0x3fb8aa3b, v43
	v_exp_f32_e32 v43, v43
	v_fma_f32 v45, v36, v40, 0
	v_fmac_f32_e32 v45, v37, v41
	v_fmac_f32_e32 v45, v38, v42
	v_fmac_f32_e32 v45, v39, v43
	v_mov_b32_e32 v250, v45
	v_mov_b32_e32 v44, v45
	s_nop 1
	v_permlane16_swap_b32_e32 v44, v250
	s_waitcnt lgkmcnt(0)
	v_add_f32_e32 v44, v250, v44
	v_mov_b32_e32 v250, v44
	v_mov_b32_e32 v45, v44
	s_nop 1
	v_permlane32_swap_b32_e32 v45, v250
	s_and_saveexec_b64 s[0:1], s[14:15]
	s_cbranch_execz .LBB0_436
	s_waitcnt lgkmcnt(0)
	v_add_f32_e32 v44, v250, v45
	ds_write_b32 v117, v44

; DEVI float bf_lo(unsigned u) { return __uint_as_float(u << 16); }
; DEVI float bf_hi(unsigned u) { return __uint_as_float(u & 0xffff0000u); }
; __device__ __forceinline__ void mlstm_item8(const Params& p, unsigned char* lds, int item) {
;     ...
;     {
;       const int t = tid >> 3, part = tid & 7; float sacc = 0.f;
; #pragma unroll
;       for (int j = 0; j < 2; ++j) { const uint4 qv = *(const uint4*)(Qs + t * 136 + part * 16 + j * 8); const float* np = nv + part * 16 + j * 8;
;         sacc += bf_lo(qv.x) * np[0] + bf_hi(qv.x) * np[1] + bf_lo(qv.y) * np[2] + bf_hi(qv.y) * np[3] + bf_lo(qv.z) * np[4] + bf_hi(qv.z) * np[5] + bf_lo(qv.w) * np[6] + bf_hi(qv.w) * np[7]; }
;       sacc += __shfl_xor(sacc, 1); sacc += __shfl_xor(sacc, 2); sacc += __shfl_xor(sacc, 4);
;       if (part == 0) qn[t] = sacc;
;     }
.LBB0_437:
	s_waitcnt lgkmcnt(1)
	ds_read_b128 v[36:39], v118
	ds_read_b128 v[42:45], v118 offset:16
	ds_read_b128 v[46:49], v119
	ds_read_b128 v[162:165], v119 offset:16
	ds_read_b128 v[166:169], v119 offset:32
	ds_read_b128 v[170:173], v119 offset:48
	s_waitcnt lgkmcnt(5)
	v_lshlrev_b32_e32 v41, 16, v36
	v_and_b32_e32 v36, 0xffff0000, v36
	s_waitcnt lgkmcnt(3)
	v_mul_f32_e32 v36, v47, v36
	v_fmac_f32_e32 v36, v46, v41
	v_lshlrev_b32_e32 v41, 16, v37
	v_fmac_f32_e32 v36, v48, v41
	v_and_b32_e32 v37, 0xffff0000, v37
	v_fmac_f32_e32 v36, v49, v37
	v_lshlrev_b32_e32 v37, 16, v38
	s_waitcnt lgkmcnt(2)
	v_fmac_f32_e32 v36, v162, v37
	v_and_b32_e32 v37, 0xffff0000, v38
	v_fmac_f32_e32 v36, v163, v37
	v_lshlrev_b32_e32 v37, 16, v39
	v_fmac_f32_e32 v36, v164, v37
	v_and_b32_e32 v37, 0xffff0000, v39
	v_and_b32_e32 v38, 0xffff0000, v42
	v_fmac_f32_e32 v36, v165, v37
	v_lshlrev_b32_e32 v37, 16, v42
	s_waitcnt lgkmcnt(1)
	v_mul_f32_e32 v38, v167, v38
	v_fmac_f32_e32 v38, v166, v37
	v_lshlrev_b32_e32 v37, 16, v43
	v_fmac_f32_e32 v38, v168, v37
	v_and_b32_e32 v37, 0xffff0000, v43
	v_fmac_f32_e32 v38, v169, v37
	v_lshlrev_b32_e32 v37, 16, v44
	s_waitcnt lgkmcnt(0)
	v_fmac_f32_e32 v38, v170, v37
	v_and_b32_e32 v37, 0xffff0000, v44
	v_fmac_f32_e32 v38, v171, v37
	v_lshlrev_b32_e32 v37, 16, v45
	v_fmac_f32_e32 v38, v172, v37
	v_and_b32_e32 v37, 0xffff0000, v45
	v_fmac_f32_e32 v38, v173, v37
	v_xor_b32_e32 v37, 1, v40
	v_cmp_lt_i32_e32 vcc, v37, v52
	v_add_f32_e32 v36, 0, v36
	v_add_f32_e32 v36, v36, v38
	v_cndmask_b32_e32 v37, v40, v37, vcc
	v_lshlrev_b32_e32 v37, 2, v37
	s_nop 1
	v_mov_b32_dpp v37, v36 quad_perm:[1,0,3,2] row_mask:0xf bank_mask:0xf
	s_waitcnt lgkmcnt(0)
	v_add_f32_e32 v36, v36, v37
	v_xor_b32_e32 v37, 2, v40
	v_cmp_lt_i32_e32 vcc, v37, v52
	s_nop 1
	v_cndmask_b32_e32 v37, v40, v37, vcc
	v_lshlrev_b32_e32 v37, 2, v37
	s_nop 1
	v_mov_b32_dpp v37, v36 quad_perm:[2,3,0,1] row_mask:0xf bank_mask:0xf
	s_waitcnt lgkmcnt(0)
	v_add_f32_e32 v36, v36, v37
	v_xor_b32_e32 v37, 4, v40
	v_cmp_lt_i32_e32 vcc, v37, v52
	s_nop 1
	v_cndmask_b32_e32 v37, v40, v37, vcc
	v_lshlrev_b32_e32 v37, 2, v37
	s_nop 1
	v_mov_b32_dpp v37, v36 row_half_mirror row_mask:0xf bank_mask:0xf
	s_and_saveexec_b64 s[0:1], s[28:29]
	s_cbranch_execz .LBB0_439
	s_waitcnt lgkmcnt(0)
	v_add_f32_e32 v36, v36, v37
	ds_write_b32 v120, v36
